# NA softmax: score+bias adds paired into v_pk_add_f32 (16 sites), row-sum zero-init dropped
# baseline (speedup 1.0000x reference)
.Lna_nodma:
	s_cmp_lt_u32 s76, s81
	s_cselect_b64 s[74:75], -1, 0
	s_cmp_gt_u32 s76, s3
	s_cselect_b64 s[76:77], -1, 0
	s_or_b64 s[74:75], s[74:75], s[76:77]
	s_and_b64 vcc, exec, s[74:75]
	s_cbranch_vccnz .LBB0_249
	s_mul_hi_u32 s11, s10, 0x24924925
	s_sub_i32 s74, s10, s11
	s_lshr_b32 s74, s74, 1
	s_add_i32 s74, s74, s11
	s_lshr_b32 s11, s74, 2
	s_mul_i32 s11, s11, 0x1c000
	s_sub_i32 s11, s78, s11
	s_add_i32 s11, s11, 0
	v_add_u32_e32 v130, s11, v158
	v_add_u32_e32 v70, v130, v154
	v_add_u32_e32 v126, v130, v159
	ds_read_b128 v[174:177], v70
	ds_read_b128 v[178:181], v70 offset:4096
	v_add_u32_e32 v131, v130, v160
	ds_read_b128 v[182:185], v126
	ds_read_b128 v[186:189], v126 offset:4096
	v_add_u32_e32 v130, v130, v161
	ds_read_b128 v[190:193], v131
	ds_read_b128 v[194:197], v131 offset:4096
	ds_read_b128 v[198:201], v130
	ds_read_b128 v[202:205], v130 offset:4096
	v_readlane_b32 s76, v252, 32
	v_readlane_b32 s77, v252, 33
	v_add_u32_e32 v168, 0, v147
	s_mov_b64 s[74:75], -1
	v_add_u32_e32 v165, 0x20670, v168
	v_add_u32_e32 v164, 0x20678, v168
	v_add_u32_e32 v167, 0x20650, v168
	v_add_u32_e32 v166, 0x20658, v168
	s_and_b64 vcc, exec, s[76:77]
	s_waitcnt lgkmcnt(7)
	v_mfma_f32_32x32x16_bf16 v[82:97], v[174:177], v[98:101], v[32:47]
	s_waitcnt lgkmcnt(6)
	v_mfma_f32_32x32x16_bf16 v[66:81], v[178:181], v[98:101], v[48:63]
	s_waitcnt lgkmcnt(5)
	v_mfma_f32_32x32x16_bf16 v[82:97], v[182:185], v[102:105], v[82:97]
	s_waitcnt lgkmcnt(4)
	v_mfma_f32_32x32x16_bf16 v[66:81], v[186:189], v[102:105], v[66:81]
	s_waitcnt lgkmcnt(3)
	v_mfma_f32_32x32x16_bf16 v[82:97], v[190:193], v[106:109], v[82:97]
	s_waitcnt lgkmcnt(2)
	v_mfma_f32_32x32x16_bf16 v[66:81], v[194:197], v[106:109], v[66:81]
	s_waitcnt lgkmcnt(1)
	v_mfma_f32_32x32x16_bf16 v[82:97], v[198:201], v[110:113], v[82:97]
	s_waitcnt lgkmcnt(0)
	v_mfma_f32_32x32x16_bf16 v[66:81], v[202:205], v[110:113], v[66:81]
	s_cbranch_vccz .LBB0_238
	v_add_u32_e32 v122, 0x20690, v168
	v_add_u32_e32 v124, 0x20698, v168
	v_add_u32_e32 v126, 0x206b0, v168
	v_add_u32_e32 v128, 0x206b8, v168
	v_add_u32_e32 v132, 0x206d0, v168
	v_add_u32_e32 v136, 0x206d8, v168
	ds_read2_b32 v[122:123], v122 offset1:1
	ds_read2_b32 v[124:125], v124 offset1:1
	ds_read2_b32 v[126:127], v126 offset1:1
	ds_read2_b32 v[128:129], v128 offset1:1
	ds_read2_b32 v[130:131], v165 offset1:1
	ds_read2_b32 v[132:133], v132 offset1:1
	ds_read2_b32 v[134:135], v164 offset1:1
	ds_read2_b32 v[136:137], v136 offset1:1
	ds_read2_b32 v[170:171], v167 offset1:1
	ds_read2_b32 v[172:173], v166 offset1:1
	s_mov_b64 s[74:75], 0
	s_waitcnt lgkmcnt(1)
	v_mov_b32_e32 v163, v170
	s_waitcnt lgkmcnt(0)
	v_mov_b32_e32 v169, v172
	s_nop 0
	v_pk_add_f32 v[130:131], v[66:67], v[130:131]
	v_exp_f32_e32 v130, v130
	v_exp_f32_e32 v131, v131
	v_pk_add_f32 v[134:135], v[68:69], v[134:135]
	v_exp_f32_e32 v134, v134
	v_exp_f32_e32 v135, v135
	v_pk_add_f32 v[70:71], v[70:71], v[122:123]
	v_exp_f32_e32 v70, v70
	v_add_f32_e32 v170, v131, v130
	v_exp_f32_e32 v71, v71
	v_pk_add_f32 v[72:73], v[72:73], v[124:125]
	v_add_f32_e32 v170, v134, v170
	v_exp_f32_e32 v72, v72
	v_add_f32_e32 v170, v135, v170
	v_exp_f32_e32 v73, v73
	v_pk_add_f32 v[74:75], v[74:75], v[126:127]
	v_add_f32_e32 v122, v70, v170
	v_exp_f32_e32 v74, v74
	v_add_f32_e32 v122, v71, v122
	v_exp_f32_e32 v75, v75
	v_pk_add_f32 v[76:77], v[76:77], v[128:129]
	v_add_f32_e32 v122, v72, v122
	v_exp_f32_e32 v76, v76
	v_add_f32_e32 v122, v73, v122
	v_exp_f32_e32 v77, v77
	v_pk_add_f32 v[78:79], v[78:79], v[132:133]
	v_add_f32_e32 v122, v74, v122
	v_exp_f32_e32 v78, v78
	v_add_f32_e32 v122, v75, v122
	v_exp_f32_e32 v79, v79
	v_pk_add_f32 v[80:81], v[80:81], v[136:137]
	v_add_f32_e32 v122, v76, v122
	v_exp_f32_e32 v80, v80
	v_add_f32_e32 v122, v77, v122
	v_exp_f32_e32 v81, v81
	v_add_f32_e32 v123, v94, v163
	v_add_f32_e32 v122, v78, v122
	v_exp_f32_e32 v123, v123
	v_add_f32_e32 v124, v95, v171
	v_add_f32_e32 v122, v79, v122
	v_exp_f32_e32 v124, v124
	v_add_f32_e32 v125, v96, v169
	v_add_f32_e32 v126, v97, v173
	v_add_f32_e32 v122, v80, v122
	v_exp_f32_e32 v125, v125
	v_exp_f32_e32 v126, v126
	v_add_f32_e32 v122, v81, v122
	v_add_f32_e32 v122, v123, v122
	v_add_f32_e32 v122, v124, v122
	v_add_f32_e32 v122, v125, v122
	v_cvt_pk_bf16_f32 v132, v123, v124
	v_cvt_pk_bf16_f32 v133, v125, v126
	v_cvt_pk_bf16_f32 v124, v78, v79
	v_cvt_pk_bf16_f32 v125, v80, v81
	v_add_f32_e32 v163, v126, v122
	v_cvt_pk_bf16_f32 v127, v134, v135
	v_cvt_pk_bf16_f32 v122, v74, v75
	v_cvt_pk_bf16_f32 v123, v76, v77
	v_mov_b64_e32 v[136:137], v[124:125]
	v_cvt_pk_bf16_f32 v126, v130, v131
	v_cvt_pk_bf16_f32 v128, v70, v71
	v_cvt_pk_bf16_f32 v129, v72, v73
	v_mov_b64_e32 v[134:135], v[122:123]
.LBB0_238:
	v_mov_b32_e32 v130, 0
	s_andn2_b64 vcc, exec, s[74:75]
	v_mov_b32_e32 v131, v130
	s_cbranch_vccnz .LBB0_240
	s_nop 6
	v_add_u32_e32 v70, 0x205f0, v168
	v_add_u32_e32 v72, 0x205f8, v168
	v_add_u32_e32 v74, 0x20610, v168
	v_add_u32_e32 v76, 0x20618, v168
	v_add_u32_e32 v78, 0x20630, v168
	v_add_u32_e32 v116, 0x20638, v168
	ds_read2_b32 v[70:71], v70 offset1:1
	ds_read2_b32 v[72:73], v72 offset1:1
	ds_read2_b32 v[74:75], v74 offset1:1
	ds_read2_b32 v[76:77], v76 offset1:1
	ds_read2_b32 v[78:79], v78 offset1:1
	ds_read2_b32 v[80:81], v167 offset1:1
	ds_read2_b32 v[114:115], v166 offset1:1
	ds_read2_b32 v[116:117], v116 offset1:1
	ds_read2_b32 v[122:123], v165 offset1:1
	ds_read2_b32 v[124:125], v164 offset1:1
	s_waitcnt lgkmcnt(0)
	s_nop 0
	v_pk_add_f32 v[70:71], v[82:83], v[70:71]
	v_exp_f32_e32 v70, v70
	v_exp_f32_e32 v71, v71
	v_pk_add_f32 v[72:73], v[84:85], v[72:73]
	v_exp_f32_e32 v72, v72
	v_exp_f32_e32 v73, v73
	v_pk_add_f32 v[74:75], v[86:87], v[74:75]
	v_exp_f32_e32 v74, v74
	v_add_f32_e32 v82, v71, v70
	v_exp_f32_e32 v75, v75
	v_pk_add_f32 v[76:77], v[88:89], v[76:77]
	v_add_f32_e32 v82, v72, v82
	v_exp_f32_e32 v76, v76
	v_add_f32_e32 v82, v73, v82
	v_exp_f32_e32 v77, v77
	v_pk_add_f32 v[78:79], v[90:91], v[78:79]
	v_add_f32_e32 v82, v74, v82
	v_exp_f32_e32 v78, v78
	v_add_f32_e32 v82, v75, v82
	v_exp_f32_e32 v79, v79
	v_add_f32_e32 v83, v92, v116
	v_add_f32_e32 v82, v76, v82
	v_exp_f32_e32 v83, v83
	v_add_f32_e32 v84, v93, v117
	v_add_f32_e32 v82, v77, v82
	v_exp_f32_e32 v84, v84
	v_pk_add_f32 v[80:81], v[94:95], v[80:81]
	v_add_f32_e32 v82, v78, v82
	v_exp_f32_e32 v80, v80
	v_add_f32_e32 v82, v79, v82
	v_exp_f32_e32 v81, v81
	v_add_f32_e32 v85, v96, v114
	v_add_f32_e32 v82, v83, v82
	v_exp_f32_e32 v85, v85
	v_add_f32_e32 v86, v97, v115
	v_add_f32_e32 v82, v84, v82
	v_exp_f32_e32 v86, v86
	v_pk_add_f32 v[66:67], v[66:67], v[122:123]
	v_add_f32_e32 v82, v80, v82
	v_exp_f32_e32 v66, v66
	v_add_f32_e32 v82, v81, v82
	v_exp_f32_e32 v67, v67
	v_pk_add_f32 v[68:69], v[68:69], v[124:125]
	v_add_f32_e32 v82, v85, v82
	v_exp_f32_e32 v68, v68
	v_add_f32_e32 v82, v86, v82
	v_exp_f32_e32 v69, v69
	v_add_f32_e32 v82, v66, v82
	v_add_f32_e32 v82, v67, v82
	v_add_f32_e32 v82, v68, v82
	v_mov_b64_e32 v[136:137], v[120:121]
	v_add_f32_e32 v163, v69, v82
	v_cvt_pk_bf16_f32 v114, v70, v71
	v_cvt_pk_bf16_f32 v115, v72, v73
	v_cvt_pk_bf16_f32 v116, v74, v75
	v_cvt_pk_bf16_f32 v117, v76, v77
	v_cvt_pk_bf16_f32 v130, v78, v79
	v_cvt_pk_bf16_f32 v131, v83, v84
	v_cvt_pk_bf16_f32 v132, v80, v81
	v_cvt_pk_bf16_f32 v133, v85, v86
	v_cvt_pk_bf16_f32 v126, v66, v67
	v_cvt_pk_bf16_f32 v127, v68, v69
	v_mov_b32_e32 v128, 0
	v_mov_b64_e32 v[134:135], v[118:119]
	v_mov_b32_e32 v122, v118
	v_mov_b32_e32 v123, v119
	v_mov_b32_e32 v124, v120
	v_mov_b32_e32 v125, v121
	v_mov_b32_e32 v129, 0
